# seam release trim: group-flag guarded write-back at seams 5,12; per-workgroup guarded write-back at chip-wide seams 3,10 (leader wbl2 dropped); XCD leader invalidates behind its top arrive and release
# speedup vs baseline: 1.0150x; 1.0054x over previous
.LBB0_151:
	s_or_b64 exec, exec, s[6:7]
	v_cvt_f32_u32_e32 v5, v3
	s_waitcnt vmcnt(0)
	v_readfirstlane_b32 s4, v4
	v_sub_u32_e32 v4, 0, v3
	v_rcp_iflag_f32_e32 v5, v5
	v_add_u32_e32 v6, s4, v2
	v_mul_f32_e32 v5, 0x4f7ffffe, v5
	v_cvt_u32_f32_e32 v5, v5
	v_mul_lo_u32 v2, v4, v5
	v_mul_hi_u32 v2, v5, v2
	v_add_u32_e32 v2, v5, v2
	v_mul_hi_u32 v2, v6, v2
	v_mul_lo_u32 v4, v2, v3
	v_sub_u32_e32 v4, v6, v4
	v_add_u32_e32 v5, 1, v2
	v_cmp_ge_u32_e32 vcc, v4, v3
	s_nop 1
	v_cndmask_b32_e32 v2, v2, v5, vcc
	v_sub_u32_e32 v5, v4, v3
	v_cndmask_b32_e32 v4, v4, v5, vcc
	v_add_u32_e32 v5, 1, v2
	v_cmp_ge_u32_e32 vcc, v4, v3
	v_add_u32_e32 v4, 1, v6
	s_nop 0
	v_cndmask_b32_e32 v2, v2, v5, vcc
	v_mul_lo_u32 v5, v3, v2
	v_add_u32_e32 v3, v5, v3
	v_cmp_ne_u32_e32 vcc, v4, v3
	s_and_saveexec_b64 s[4:5], vcc
	s_xor_b64 s[4:5], exec, s[4:5]
	s_cbranch_execz .LBB0_165
	s_waitcnt lgkmcnt(0)
	v_mov_b32_e32 v1, 0x2000
	global_load_dword v1, v1, s[2:3] offset:1024 sc1
	buffer_inv sc1
	s_add_u32 s10, s2, 0x2400
	s_addc_u32 s11, s3, 0
	s_waitcnt vmcnt(0)
	v_cmp_eq_u32_e32 vcc, v1, v2
	s_and_saveexec_b64 s[6:7], vcc
	s_cbranch_execz .LBB0_164
	s_add_u32 s8, s82, 0x4200
	s_addc_u32 s9, s83, 0
	s_mov_b32 s22, 1
	s_mov_b64 s[12:13], 0
	v_mov_b32_e32 v1, 0
	s_branch .LBB0_155

.LBB0_168:
	s_or_b64 exec, exec, s[6:7]
	buffer_inv sc1
	v_cvt_f32_u32_e32 v4, v1
	s_waitcnt vmcnt(1)
	v_readfirstlane_b32 s4, v3
	s_add_u32 s6, s82, 0x7500
	s_addc_u32 s7, s83, 0
	v_rcp_iflag_f32_e32 v4, v4
	v_add_u32_e32 v2, s4, v2
	v_add_u32_e32 v5, 1, v2
	s_mov_b64 s[8:9], -1
	v_mul_f32_e32 v3, 0x4f7ffffe, v4
	v_cvt_u32_f32_e32 v3, v3
	v_sub_u32_e32 v4, 0, v1
	v_mul_lo_u32 v4, v4, v3
	v_mul_hi_u32 v4, v3, v4
	v_add_u32_e32 v3, v3, v4
	v_mul_hi_u32 v3, v2, v3
	v_mul_lo_u32 v4, v3, v1
	v_sub_u32_e32 v2, v2, v4
	v_add_u32_e32 v6, 1, v3
	v_cmp_ge_u32_e32 vcc, v2, v1
	v_sub_u32_e32 v4, v2, v1
	s_nop 0
	v_cndmask_b32_e32 v3, v3, v6, vcc
	v_cndmask_b32_e32 v2, v2, v4, vcc
	v_add_u32_e32 v4, 1, v3
	v_cmp_ge_u32_e32 vcc, v2, v1
	s_nop 1
	v_cndmask_b32_e32 v4, v3, v4, vcc
	v_mul_lo_u32 v2, v1, v4
	v_add_u32_e32 v1, v2, v1
	v_cmp_ne_u32_e32 vcc, v5, v1
	v_mov_b64_e32 v[2:3], s[6:7]
	s_and_saveexec_b64 s[4:5], vcc
	s_cbranch_execz .LBB0_180
	v_mov_b32_e32 v1, 0
	global_load_dword v2, v1, s[6:7] sc1
	s_mov_b64 s[12:13], 0
	s_waitcnt vmcnt(0)
	v_cmp_eq_u32_e32 vcc, v2, v4
	s_and_saveexec_b64 s[10:11], vcc
	s_cbranch_execz .LBB0_179
	s_add_u32 s8, s82, 0x4200
	s_addc_u32 s9, s83, 0
	s_mov_b32 s22, 1
	s_branch .LBB0_172

.LBB0_182:
	s_or_b64 exec, exec, s[4:5]
	s_mov_b64 s[4:5], exec
	v_mbcnt_lo_u32_b32 v1, s4, 0
	v_mbcnt_hi_u32_b32 v1, s5, v1
	v_cmp_eq_u32_e32 vcc, 0, v1
	s_and_saveexec_b64 s[6:7], vcc
	s_cbranch_execz .LBB0_184
	s_bcnt1_i32_b64 s4, s[4:5]
	v_mov_b32_e32 v1, 0x2000
	v_mov_b32_e32 v2, s4
	global_atomic_add v1, v2, s[2:3] offset:1024

.LBB0_788:
	s_mov_b64 s[4:5], exec
	v_readlane_b32 s2, v249, 9
	s_lshl_b32 s2, s2, 8
	v_readlane_b32 s6, v249, 7
	v_mbcnt_lo_u32_b32 v2, s4, 0
	v_readlane_b32 s7, v249, 8
	s_add_u32 s2, s6, s2
	v_mbcnt_hi_u32_b32 v2, s5, v2
	s_addc_u32 s3, s7, 0
	v_cmp_eq_u32_e32 vcc, 0, v2
	s_and_saveexec_b64 s[6:7], vcc
	s_cbranch_execz .LBB0_790
	v_readlane_b32 s98, v250, 0
	s_cmp_lg_u32 s98, 0
	s_cbranch_scc1 .Lxw_3
	buffer_wbl2 sc1
	s_waitcnt vmcnt(0)
.Lxw_3:
	s_bcnt1_i32_b64 s4, s[4:5]
	v_mov_b32_e32 v4, 0x1000
	v_mov_b32_e32 v5, s4
	global_atomic_add v4, v4, v5, s[2:3] offset:1024 sc0

.LBB0_804:
	s_andn2_saveexec_b64 s[4:5], s[4:5]
	s_cbranch_execz .LBB0_824
	s_mov_b64 s[4:5], exec
	s_waitcnt lgkmcnt(0)
	s_waitcnt vmcnt(0)
	v_mbcnt_lo_u32_b32 v2, s4, 0
	v_mbcnt_hi_u32_b32 v2, s5, v2
	v_cmp_eq_u32_e32 vcc, 0, v2
	s_and_saveexec_b64 s[6:7], vcc
	s_cbranch_execz .LBB0_807
	s_bcnt1_i32_b64 s4, s[4:5]
	v_mov_b32_e32 v3, 0x7000
	v_mov_b32_e32 v4, s4
	global_atomic_add v3, v3, v4, s[82:83] offset:1024 sc0

.LBB0_1126:
	v_readlane_b32 s0, v249, 4
	v_readlane_b32 s1, v249, 5
	s_cmp_lt_i32 s1, 7
	s_mov_b64 s[0:1], -1
	s_cbranch_scc0 .LBB0_1128
	s_waitcnt vmcnt(0) lgkmcnt(0)
	s_barrier
	s_mov_b64 s[0:1], 0
.LBB0_1128:
	s_andn2_b64 vcc, exec, s[0:1]
	s_cbranch_vccnz .LBB0_1195
	v_readlane_b32 s0, v249, 4
	v_readlane_b32 s1, v249, 5
	s_cmpk_lt_u32 s1, 0x3e9
	s_mov_b64 s[0:1], -1
	s_cbranch_scc0 .LBB0_1183
	v_readlane_b32 s2, v249, 2
	s_cmpk_eq_i32 s2, 0x100
	s_cbranch_scc0 .Lg5_xcd
	s_waitcnt vmcnt(0)
	s_waitcnt vmcnt(0) lgkmcnt(0)
	s_barrier
	s_mov_b64 s[0:1], exec
	v_readlane_b32 s2, v249, 10
	v_readlane_b32 s3, v249, 11
	s_and_b64 s[2:3], s[0:1], s[2:3]
	s_mov_b64 exec, s[2:3]
	s_cbranch_execz .Lg5_BB0_1004
	s_lshl_b32 s2, s81, 8
	s_and_b32 s2, s2, 0x3f00
	s_mov_b64 s[4:5], exec
	s_add_u32 s2, s82, s2
	s_addc_u32 s3, s83, 0
	v_readlane_b32 s98, v250, 0
	s_cmp_lg_u32 s98, 0
	s_cbranch_scc1 .Lg5_skip_wbl2_2
	buffer_wbl2 sc1

.LBB0_2262:
	v_readlane_b32 s0, v249, 4
	v_readlane_b32 s1, v249, 5
	s_cmp_lt_i32 s1, 14
	s_mov_b64 s[0:1], -1
	s_cbranch_scc0 .LBB0_2264
	s_waitcnt vmcnt(0) lgkmcnt(0)
	s_barrier
	s_mov_b64 s[0:1], 0
.LBB0_2264:
	s_andn2_b64 vcc, exec, s[0:1]
	s_cbranch_vccnz .LBB0_2331
	v_readlane_b32 s0, v249, 4
	v_readlane_b32 s1, v249, 5
	s_cmpk_lt_u32 s1, 0x3e9
	s_mov_b64 s[0:1], -1
	s_cbranch_scc0 .LBB0_2319
	v_readlane_b32 s2, v249, 2
	s_cmpk_eq_i32 s2, 0x100
	s_cbranch_scc0 .Lg12_xcd
	s_waitcnt vmcnt(0)
	s_waitcnt vmcnt(0) lgkmcnt(0)
	s_barrier
	s_mov_b64 s[0:1], exec
	v_readlane_b32 s2, v249, 10
	v_readlane_b32 s3, v249, 11
	s_and_b64 s[2:3], s[0:1], s[2:3]
	s_mov_b64 exec, s[2:3]
	s_cbranch_execz .Lg12_BB0_1004
	s_lshl_b32 s2, s81, 8
	s_and_b32 s2, s2, 0x3f00
	s_mov_b64 s[4:5], exec
	s_add_u32 s2, s82, s2
	s_addc_u32 s3, s83, 0
	v_readlane_b32 s98, v250, 0
	s_cmp_lg_u32 s98, 0
	s_cbranch_scc1 .Lg12_skip_wbl2_2
	buffer_wbl2 sc1
